# attention unit epilogue: 16 subln loads prefetched, exact counted vmcnt instead of vmcnt(0) behind every 8-byte store
# baseline (speedup 1.0000x reference)
; __device__ __forceinline__ void swap32(float& a, float& b) { asm volatile("s_nop 1\n\tv_permlane32_swap_b32 %0, %1\n\ts_nop 1" : "+v"(a), "+v"(b)); }
; __device__ __forceinline__ int crow(int r, int hi) { return (r & 3) + 8 * (r >> 2) + 4 * hi; }
; __device__ __forceinline__ void unit(const Ctx& C, int xq, int idx, LAS unsigned char* lds) {
;     ...
;     if (mp == 0 && valid) {
;         float ss = 0.f;
; #pragma unroll
;         for (int i = 0; i < 4; ++i)
; #pragma unroll
;             for (int r = 0; r < 16; ++r) { const float o = O[i][r] * inv - C.lam * X[(32 * i + crow(r, hi)) * 32 + q]; O[i][r] = o; ss += o * o; }
;         { float ra = ss, rbv = ss; swap32(ra, rbv); ss = ra + rbv; }
;         const float rn = __builtin_amdgcn_rsqf(ss * (1.0f / DV) + EPS) * 0.8f;
.LBB0_552:
	s_cmpk_lt_u32 s83, 0x100
	s_cselect_b64 s[34:35], -1, 0
	s_and_b64 s[34:35], s[34:35], s[42:43]
	s_andn2_b64 vcc, exec, s[34:35]
	s_waitcnt lgkmcnt(0)
	s_barrier
	s_cbranch_vccnz .LBB0_479
	global_load_dwordx4 v[138:141], v[188:189], off
	global_load_dwordx4 v[142:145], v[188:189], off offset:32
	global_load_dwordx4 v[146:149], v[188:189], off offset:64
	global_load_dwordx4 v[150:153], v[188:189], off offset:96
	global_load_dwordx4 v[154:157], v[188:189], off offset:128
	global_load_dwordx4 v[216:219], v[188:189], off offset:160
	global_load_dwordx4 v[222:225], v[188:189], off offset:192
	global_load_dwordx4 v[226:229], v[188:189], off offset:224
	global_load_dwordx4 v[230:233], v[188:189], off offset:256
	global_load_dwordx4 v[234:237], v[188:189], off offset:288
	global_load_dwordx4 v[238:241], v[188:189], off offset:320
	global_load_dwordx4 v[242:245], v[188:189], off offset:352
	global_load_dwordx4 v[246:249], v[188:189], off offset:384
	v_lshlrev_b32_e32 v65, 2, v201
	v_add3_u32 v65, s0, v209, v65
	v_add_u32_e32 v66, 0x400, v65
	ds_read2_b32 v[68:69], v65 offset1:32
	ds_read2_b32 v[72:73], v65 offset0:64 offset1:96
	ds_read2_b32 v[74:75], v66 offset1:32
	ds_read2_b32 v[76:77], v66 offset0:64 offset1:96
	v_add_u32_e32 v66, 0x800, v65
	ds_read2_b32 v[78:79], v66 offset1:32
	ds_read2_b32 v[80:81], v66 offset0:64 offset1:96
	v_add_u32_e32 v66, 0xc00, v65
	ds_read2_b32 v[82:83], v66 offset1:32
	ds_read2_b32 v[84:85], v66 offset0:64 offset1:96
	v_add_u32_e32 v66, 0x1000, v65
	ds_read2_b32 v[86:87], v66 offset1:32
	ds_read2_b32 v[88:89], v66 offset0:64 offset1:96
	v_add_u32_e32 v66, 0x1400, v65
	ds_read2_b32 v[90:91], v66 offset1:32
	ds_read2_b32 v[92:93], v66 offset0:64 offset1:96
	v_add_u32_e32 v66, 0x1800, v65
	ds_read2_b32 v[94:95], v66 offset1:32
	ds_read2_b32 v[96:97], v66 offset0:64 offset1:96
	v_add_u32_e32 v66, 0x1c00, v65
	ds_read2_b32 v[98:99], v66 offset1:32
	ds_read2_b32 v[100:101], v66 offset0:64 offset1:96
	v_add_u32_e32 v66, 0x2000, v65
	ds_read2_b32 v[102:103], v66 offset1:32
	ds_read2_b32 v[104:105], v66 offset0:64 offset1:96
	v_add_u32_e32 v66, 0x2400, v65
	ds_read2_b32 v[106:107], v66 offset1:32
	ds_read2_b32 v[108:109], v66 offset0:64 offset1:96
	v_add_u32_e32 v66, 0x2800, v65
	ds_read2_b32 v[110:111], v66 offset1:32
	ds_read2_b32 v[112:113], v66 offset0:64 offset1:96
	v_add_u32_e32 v66, 0x2c00, v65
	ds_read2_b32 v[114:115], v66 offset1:32
	ds_read2_b32 v[116:117], v66 offset0:64 offset1:96
	v_add_u32_e32 v66, 0x3000, v65
	ds_read2_b32 v[118:119], v66 offset1:32
	ds_read2_b32 v[120:121], v66 offset0:64 offset1:96
	v_add_u32_e32 v66, 0x3400, v65
	v_add_u32_e32 v70, 0x3c00, v65
	v_add_u32_e32 v65, 0x3800, v65
	s_waitcnt lgkmcnt(14)
	v_pk_mul_f32 v[68:69], v[182:183], v[68:69]
	v_pk_mul_f32 v[72:73], v[182:183], v[72:73]
	v_pk_fma_f32 v[68:69], v[48:49], v[64:65], v[68:69] op_sel_hi:[1,0,1] neg_lo:[0,0,1] neg_hi:[0,0,1]
	v_pk_mul_f32 v[48:49], v[182:183], v[76:77]
	v_pk_fma_f32 v[50:51], v[50:51], v[64:65], v[72:73] op_sel_hi:[1,0,1] neg_lo:[0,0,1] neg_hi:[0,0,1]
	v_pk_fma_f32 v[48:49], v[54:55], v[64:65], v[48:49] op_sel_hi:[1,0,1] neg_lo:[0,0,1] neg_hi:[0,0,1]
	v_pk_mul_f32 v[54:55], v[182:183], v[74:75]
	ds_read2_b32 v[122:123], v66 offset1:32
	ds_read2_b32 v[124:125], v66 offset0:64 offset1:96
	v_pk_fma_f32 v[72:73], v[52:53], v[64:65], v[54:55] op_sel_hi:[1,0,1] neg_lo:[0,0,1] neg_hi:[0,0,1]
	v_pk_mul_f32 v[54:55], v[182:183], v[78:79]
	v_pk_mul_f32 v[52:53], v[182:183], v[80:81]
	v_pk_fma_f32 v[74:75], v[56:57], v[64:65], v[54:55] op_sel_hi:[1,0,1] neg_lo:[0,0,1] neg_hi:[0,0,1]
	v_pk_mul_f32 v[56:57], v[182:183], v[82:83]
	v_pk_fma_f32 v[52:53], v[58:59], v[64:65], v[52:53] op_sel_hi:[1,0,1] neg_lo:[0,0,1] neg_hi:[0,0,1]
	v_pk_fma_f32 v[76:77], v[60:61], v[64:65], v[56:57] op_sel_hi:[1,0,1] neg_lo:[0,0,1] neg_hi:[0,0,1]
	v_pk_mul_f32 v[56:57], v[182:183], v[88:89]
	v_pk_mul_f32 v[54:55], v[182:183], v[84:85]
	v_pk_fma_f32 v[56:57], v[34:35], v[64:65], v[56:57] op_sel_hi:[1,0,1] neg_lo:[0,0,1] neg_hi:[0,0,1]
	v_pk_mul_f32 v[34:35], v[182:183], v[86:87]
	ds_read2_b32 v[66:67], v70 offset1:32
	v_pk_fma_f32 v[58:59], v[32:33], v[64:65], v[34:35] op_sel_hi:[1,0,1] neg_lo:[0,0,1] neg_hi:[0,0,1]
	v_pk_mul_f32 v[32:33], v[182:183], v[92:93]
	v_pk_mul_f32 v[34:35], v[182:183], v[90:91]
	v_pk_fma_f32 v[32:33], v[38:39], v[64:65], v[32:33] op_sel_hi:[1,0,1] neg_lo:[0,0,1] neg_hi:[0,0,1]
	s_waitcnt lgkmcnt(14)
	v_pk_mul_f32 v[38:39], v[182:183], v[98:99]
	v_pk_fma_f32 v[60:61], v[36:37], v[64:65], v[34:35] op_sel_hi:[1,0,1] neg_lo:[0,0,1] neg_hi:[0,0,1]
	v_pk_fma_f32 v[44:45], v[44:45], v[64:65], v[38:39] op_sel_hi:[1,0,1] neg_lo:[0,0,1] neg_hi:[0,0,1]
	s_waitcnt lgkmcnt(11)
	v_pk_mul_f32 v[38:39], v[182:183], v[104:105]
	v_pk_mul_f32 v[36:37], v[182:183], v[94:95]
	v_pk_fma_f32 v[38:39], v[18:19], v[64:65], v[38:39] op_sel_hi:[1,0,1] neg_lo:[0,0,1] neg_hi:[0,0,1]
	v_pk_mul_f32 v[18:19], v[182:183], v[102:103]
	ds_read2_b32 v[126:127], v65 offset1:32
	ds_read2_b32 v[70:71], v70 offset0:64 offset1:96
	ds_read2_b32 v[128:129], v65 offset0:64 offset1:96
	v_pk_fma_f32 v[54:55], v[62:63], v[64:65], v[54:55] op_sel_hi:[1,0,1] neg_lo:[0,0,1] neg_hi:[0,0,1]
	v_pk_fma_f32 v[62:63], v[40:41], v[64:65], v[36:37] op_sel_hi:[1,0,1] neg_lo:[0,0,1] neg_hi:[0,0,1]
	v_pk_fma_f32 v[40:41], v[16:17], v[64:65], v[18:19] op_sel_hi:[1,0,1] neg_lo:[0,0,1] neg_hi:[0,0,1]
	s_waitcnt lgkmcnt(12)
	v_pk_mul_f32 v[16:17], v[182:183], v[108:109]
	v_pk_mul_f32 v[34:35], v[182:183], v[96:97]
	v_pk_fma_f32 v[16:17], v[22:23], v[64:65], v[16:17] op_sel_hi:[1,0,1] neg_lo:[0,0,1] neg_hi:[0,0,1]
	s_waitcnt lgkmcnt(9)
; __device__ __forceinline__ void swap32(float& a, float& b) { asm volatile("s_nop 1\n\tv_permlane32_swap_b32 %0, %1\n\ts_nop 1" : "+v"(a), "+v"(b)); }
; __device__ __forceinline__ int crow(int r, int hi) { return (r & 3) + 8 * (r >> 2) + 4 * hi; }
; __device__ __forceinline__ void unit(const Ctx& C, int xq, int idx, LAS unsigned char* lds) {
;     ...
;             for (int r = 0; r < 16; ++r) { const float o = O[i][r] * inv - C.lam * X[(32 * i + crow(r, hi)) * 32 + q]; O[i][r] = o; ss += o * o; }
;         { float ra = ss, rbv = ss; swap32(ra, rbv); ss = ra + rbv; }
;         const float rn = __builtin_amdgcn_rsqf(ss * (1.0f / DV) + EPS) * 0.8f;
;         bf16_t* op = C.oob + (size_t)qrow * DM + h * 128;
	v_pk_mul_f32 v[22:23], v[182:183], v[114:115]
	v_pk_mul_f32 v[18:19], v[182:183], v[106:107]
	v_pk_fma_f32 v[28:29], v[28:29], v[64:65], v[22:23] op_sel_hi:[1,0,1] neg_lo:[0,0,1] neg_hi:[0,0,1]
	s_waitcnt lgkmcnt(6)
	v_pk_mul_f32 v[22:23], v[182:183], v[120:121]
	v_pk_fma_f32 v[34:35], v[42:43], v[64:65], v[34:35] op_sel_hi:[1,0,1] neg_lo:[0,0,1] neg_hi:[0,0,1]
	v_pk_fma_f32 v[42:43], v[20:21], v[64:65], v[18:19] op_sel_hi:[1,0,1] neg_lo:[0,0,1] neg_hi:[0,0,1]
	v_pk_mul_f32 v[18:19], v[182:183], v[112:113]
	v_pk_mul_f32 v[20:21], v[182:183], v[110:111]
	v_pk_fma_f32 v[22:23], v[2:3], v[64:65], v[22:23] op_sel_hi:[1,0,1] neg_lo:[0,0,1] neg_hi:[0,0,1]
	v_pk_mul_f32 v[2:3], v[182:183], v[118:119]
	v_pk_fma_f32 v[18:19], v[26:27], v[64:65], v[18:19] op_sel_hi:[1,0,1] neg_lo:[0,0,1] neg_hi:[0,0,1]
	v_pk_fma_f32 v[26:27], v[24:25], v[64:65], v[20:21] op_sel_hi:[1,0,1] neg_lo:[0,0,1] neg_hi:[0,0,1]
	v_pk_fma_f32 v[24:25], v[0:1], v[64:65], v[2:3] op_sel_hi:[1,0,1] neg_lo:[0,0,1] neg_hi:[0,0,1]
	s_waitcnt lgkmcnt(4)
	v_pk_mul_f32 v[0:1], v[182:183], v[124:125]
	v_pk_mul_f32 v[2:3], v[182:183], v[122:123]
	s_waitcnt lgkmcnt(3)
	v_pk_mul_f32 v[66:67], v[182:183], v[66:67]
	s_waitcnt lgkmcnt(1)
	v_pk_mul_f32 v[70:71], v[182:183], v[70:71]
	v_pk_mul_f32 v[132:133], v[68:69], v[68:69]
	v_pk_mul_f32 v[36:37], v[182:183], v[100:101]
	v_pk_mul_f32 v[20:21], v[182:183], v[116:117]
	v_pk_fma_f32 v[0:1], v[6:7], v[64:65], v[0:1] op_sel_hi:[1,0,1] neg_lo:[0,0,1] neg_hi:[0,0,1]
	v_pk_fma_f32 v[4:5], v[4:5], v[64:65], v[2:3] op_sel_hi:[1,0,1] neg_lo:[0,0,1] neg_hi:[0,0,1]
	s_waitcnt lgkmcnt(0)
	v_pk_mul_f32 v[2:3], v[182:183], v[128:129]
	v_pk_mul_f32 v[6:7], v[182:183], v[126:127]
	v_pk_fma_f32 v[12:13], v[12:13], v[64:65], v[66:67] op_sel_hi:[1,0,1] neg_lo:[0,0,1] neg_hi:[0,0,1]
	v_pk_fma_f32 v[14:15], v[14:15], v[64:65], v[70:71] op_sel_hi:[1,0,1] neg_lo:[0,0,1] neg_hi:[0,0,1]
	v_pk_mul_f32 v[130:131], v[50:51], v[50:51]
	v_pk_fma_f32 v[36:37], v[46:47], v[64:65], v[36:37] op_sel_hi:[1,0,1] neg_lo:[0,0,1] neg_hi:[0,0,1]
	v_pk_fma_f32 v[20:21], v[30:31], v[64:65], v[20:21] op_sel_hi:[1,0,1] neg_lo:[0,0,1] neg_hi:[0,0,1]
	v_pk_fma_f32 v[2:3], v[10:11], v[64:65], v[2:3] op_sel_hi:[1,0,1] neg_lo:[0,0,1] neg_hi:[0,0,1]
	v_pk_fma_f32 v[6:7], v[8:9], v[64:65], v[6:7] op_sel_hi:[1,0,1] neg_lo:[0,0,1] neg_hi:[0,0,1]
	v_add_f32_e32 v64, v132, v133
	v_add_f32_e32 v64, v64, v130
	v_pk_mul_f32 v[136:137], v[72:73], v[72:73]
	v_add_f32_e32 v64, v64, v131
	v_add_f32_e32 v64, v64, v136
	v_pk_mul_f32 v[134:135], v[48:49], v[48:49]
	v_add_f32_e32 v64, v64, v137
	v_add_f32_e32 v64, v64, v134
	v_pk_mul_f32 v[78:79], v[74:75], v[74:75]
	v_add_f32_e32 v64, v64, v135
	v_add_f32_e32 v64, v64, v78
	v_pk_mul_f32 v[80:81], v[52:53], v[52:53]
	v_add_f32_e32 v64, v64, v79
	v_add_f32_e32 v64, v64, v80
	v_pk_mul_f32 v[82:83], v[76:77], v[76:77]
	v_add_f32_e32 v64, v64, v81
	v_add_f32_e32 v64, v64, v82
	v_pk_mul_f32 v[84:85], v[54:55], v[54:55]
	v_add_f32_e32 v64, v64, v83
	v_add_f32_e32 v64, v64, v84
	v_pk_mul_f32 v[86:87], v[58:59], v[58:59]
	v_add_f32_e32 v64, v64, v85
	v_add_f32_e32 v64, v64, v86
	v_pk_mul_f32 v[88:89], v[56:57], v[56:57]
	v_add_f32_e32 v64, v64, v87
	v_add_f32_e32 v64, v64, v88
	v_pk_mul_f32 v[90:91], v[60:61], v[60:61]
	v_add_f32_e32 v64, v64, v89
	v_add_f32_e32 v64, v64, v90
	v_pk_mul_f32 v[92:93], v[32:33], v[32:33]
	v_add_f32_e32 v64, v64, v91
	v_add_f32_e32 v64, v64, v92
	v_pk_mul_f32 v[94:95], v[62:63], v[62:63]
	v_add_f32_e32 v64, v64, v93
	v_add_f32_e32 v64, v64, v94
	v_pk_mul_f32 v[96:97], v[34:35], v[34:35]
	v_add_f32_e32 v64, v64, v95
	v_add_f32_e32 v64, v64, v96
	v_pk_mul_f32 v[98:99], v[44:45], v[44:45]
	v_add_f32_e32 v64, v64, v97
	v_add_f32_e32 v64, v64, v98
	v_pk_mul_f32 v[46:47], v[36:37], v[36:37]
	v_add_f32_e32 v64, v64, v99
	v_add_f32_e32 v46, v64, v46
	v_pk_mul_f32 v[102:103], v[40:41], v[40:41]
	v_add_f32_e32 v46, v46, v47
	v_add_f32_e32 v46, v46, v102
	v_pk_mul_f32 v[100:101], v[38:39], v[38:39]
	v_add_f32_e32 v46, v46, v103
	v_add_f32_e32 v46, v46, v100
	v_pk_mul_f32 v[106:107], v[42:43], v[42:43]
	v_add_f32_e32 v46, v46, v101
	v_add_f32_e32 v46, v46, v106
	v_pk_mul_f32 v[104:105], v[16:17], v[16:17]
	v_add_f32_e32 v46, v46, v107
	v_add_f32_e32 v46, v46, v104
	v_pk_mul_f32 v[110:111], v[26:27], v[26:27]
	v_add_f32_e32 v46, v46, v105
	v_add_f32_e32 v46, v46, v110
	v_pk_mul_f32 v[108:109], v[18:19], v[18:19]
	v_add_f32_e32 v46, v46, v111
	v_add_f32_e32 v46, v46, v108
	v_pk_mul_f32 v[112:113], v[28:29], v[28:29]
	v_add_f32_e32 v46, v46, v109
	v_add_f32_e32 v46, v46, v112
	v_pk_mul_f32 v[30:31], v[20:21], v[20:21]
	v_add_f32_e32 v46, v46, v113
	v_add_f32_e32 v30, v46, v30
	v_pk_mul_f32 v[116:117], v[24:25], v[24:25]
	v_add_f32_e32 v30, v30, v31
	v_add_f32_e32 v30, v30, v116
	v_pk_mul_f32 v[114:115], v[22:23], v[22:23]
	v_add_f32_e32 v30, v30, v117
	v_add_f32_e32 v30, v30, v114
	v_pk_mul_f32 v[120:121], v[4:5], v[4:5]
	v_add_f32_e32 v30, v30, v115
	v_add_f32_e32 v30, v30, v120
	v_pk_mul_f32 v[118:119], v[0:1], v[0:1]
	v_add_f32_e32 v30, v30, v121
	v_add_f32_e32 v30, v30, v118
	v_pk_mul_f32 v[8:9], v[6:7], v[6:7]
	v_add_f32_e32 v30, v30, v119
	v_add_f32_e32 v8, v30, v8
	v_pk_mul_f32 v[10:11], v[2:3], v[2:3]
	v_add_f32_e32 v8, v8, v9
	v_add_f32_e32 v8, v8, v10
	v_pk_mul_f32 v[66:67], v[12:13], v[12:13]
	v_add_f32_e32 v8, v8, v11
	v_add_f32_e32 v8, v8, v66
	v_pk_mul_f32 v[70:71], v[14:15], v[14:15]
	v_add_f32_e32 v8, v8, v67
	v_add_f32_e32 v8, v8, v70
	v_add_f32_e32 v46, v8, v71
	v_mov_b32_e32 v47, v46
	s_nop 1
	v_permlane32_swap_b32 v46, v47
	s_nop 1
	v_add_f32_e32 v46, v46, v47
	v_fmamk_f32 v46, v46, 0x3c000000, v211
	v_rsq_f32_e32 v46, v46
	v_lshlrev_b64 v[30:31], 12, v[194:195]
	v_lshl_add_u64 v[30:31], s[30:31], 0, v[30:31]
	s_mov_b32 s37, s5
	v_mul_f32_e32 v46, 0x3f4ccccd, v46
	v_pk_mul_f32 v[64:65], v[68:69], v[46:47] op_sel_hi:[1,0]
	v_pk_mul_f32 v[50:51], v[50:51], v[46:47] op_sel_hi:[1,0]
	v_lshl_add_u64 v[30:31], v[30:31], 0, s[36:37]
	v_mov_b32_e32 v193, v185
	v_lshl_add_u64 v[30:31], v[30:31], 0, v[192:193]
	v_pk_mul_f32 v[48:49], v[48:49], v[46:47] op_sel_hi:[1,0]
	v_pk_mul_f32 v[32:33], v[32:33], v[46:47] op_sel_hi:[1,0]
	v_pk_mul_f32 v[34:35], v[34:35], v[46:47] op_sel_hi:[1,0]
	v_pk_mul_f32 v[16:17], v[16:17], v[46:47] op_sel_hi:[1,0]
	v_pk_mul_f32 v[18:19], v[18:19], v[46:47] op_sel_hi:[1,0]
	v_pk_mul_f32 v[4:5], v[4:5], v[46:47] op_sel_hi:[1,0]
	v_pk_mul_f32 v[0:1], v[0:1], v[46:47] op_sel_hi:[1,0]
	v_pk_mul_f32 v[2:3], v[2:3], v[46:47] op_sel_hi:[1,0]
	s_waitcnt vmcnt(12)
; __device__ __forceinline__ unsigned cvtpk(float lo, float hi) { f32x2_t v = {lo, hi}; bf16x2_t b = __builtin_convertvector(v, bf16x2_t); return __builtin_bit_cast(unsigned, b); }
; __device__ __forceinline__ void unit(const Ctx& C, int xq, int idx, LAS unsigned char* lds) {
;     ...
; #pragma unroll
;         for (int i = 0; i < 4; ++i)
; #pragma unroll
;             for (int g4 = 0; g4 < 4; ++g4) {
;                 const int dv0 = 32 * i + 8 * g4 + 4 * hi; const f32x4 sg = *(const f32x4*)(C.subln + dv0);
;                 u32x2 w; w.x = cvtpk(O[i][4 * g4 + 0] * rn * sg[0], O[i][4 * g4 + 1] * rn * sg[1]); w.y = cvtpk(O[i][4 * g4 + 2] * rn * sg[2], O[i][4 * g4 + 3] * rn * sg[3]);
;                 *(u32x2*)(op + dv0) = w;
;             }
	v_pk_mul_f32 v[8:9], v[138:139], v[64:65]
	v_pk_mul_f32 v[10:11], v[140:141], v[50:51]
	v_cvt_pk_bf16_f32 v8, v8, v9
	v_cvt_pk_bf16_f32 v9, v10, v11
	global_store_dwordx2 v[30:31], v[8:9], off
	v_pk_mul_f32 v[50:51], v[72:73], v[46:47] op_sel_hi:[1,0]
	s_waitcnt vmcnt(12)
	v_pk_mul_f32 v[10:11], v[144:145], v[48:49]
	v_pk_mul_f32 v[8:9], v[142:143], v[50:51]
	v_pk_mul_f32 v[48:49], v[74:75], v[46:47] op_sel_hi:[1,0]
	v_cvt_pk_bf16_f32 v8, v8, v9
	v_cvt_pk_bf16_f32 v9, v10, v11
	global_store_dwordx2 v[30:31], v[8:9], off offset:16
	v_pk_mul_f32 v[50:51], v[52:53], v[46:47] op_sel_hi:[1,0]
	s_waitcnt vmcnt(12)
	v_pk_mul_f32 v[8:9], v[146:147], v[48:49]
	v_pk_mul_f32 v[10:11], v[148:149], v[50:51]
	v_cvt_pk_bf16_f32 v8, v8, v9
	v_cvt_pk_bf16_f32 v9, v10, v11
	global_store_dwordx2 v[30:31], v[8:9], off offset:32
	global_load_dwordx4 v[138:141], v[188:189], off offset:416
	global_load_dwordx4 v[142:145], v[188:189], off offset:448
	global_load_dwordx4 v[146:149], v[188:189], off offset:480
	v_pk_mul_f32 v[48:49], v[76:77], v[46:47] op_sel_hi:[1,0]
	v_pk_mul_f32 v[50:51], v[54:55], v[46:47] op_sel_hi:[1,0]
	s_waitcnt vmcnt(15)
	v_pk_mul_f32 v[8:9], v[48:49], v[150:151]
	v_pk_mul_f32 v[10:11], v[50:51], v[152:153]
	v_cvt_pk_bf16_f32 v8, v8, v9
	v_cvt_pk_bf16_f32 v9, v10, v11
	global_store_dwordx2 v[30:31], v[8:9], off offset:48
	v_pk_mul_f32 v[48:49], v[58:59], v[46:47] op_sel_hi:[1,0]
	v_pk_mul_f32 v[50:51], v[56:57], v[46:47] op_sel_hi:[1,0]
	s_waitcnt vmcnt(15)
	v_pk_mul_f32 v[8:9], v[48:49], v[154:155]
	v_pk_mul_f32 v[10:11], v[50:51], v[156:157]
	v_cvt_pk_bf16_f32 v8, v8, v9
	v_cvt_pk_bf16_f32 v9, v10, v11
	global_store_dwordx2 v[30:31], v[8:9], off offset:64
	v_pk_mul_f32 v[48:49], v[60:61], v[46:47] op_sel_hi:[1,0]
	s_waitcnt vmcnt(15)
	v_pk_mul_f32 v[10:11], v[32:33], v[218:219]
	v_pk_mul_f32 v[8:9], v[48:49], v[216:217]
	v_pk_mul_f32 v[32:33], v[62:63], v[46:47] op_sel_hi:[1,0]
	v_cvt_pk_bf16_f32 v8, v8, v9
	v_cvt_pk_bf16_f32 v9, v10, v11
	global_store_dwordx2 v[30:31], v[8:9], off offset:80
	s_waitcnt vmcnt(15)
	v_pk_mul_f32 v[8:9], v[32:33], v[222:223]
	v_pk_mul_f32 v[10:11], v[34:35], v[224:225]
	v_cvt_pk_bf16_f32 v8, v8, v9
	v_cvt_pk_bf16_f32 v9, v10, v11
	global_store_dwordx2 v[30:31], v[8:9], off offset:96
	v_pk_mul_f32 v[32:33], v[44:45], v[46:47] op_sel_hi:[1,0]
	v_pk_mul_f32 v[34:35], v[36:37], v[46:47] op_sel_hi:[1,0]
	s_waitcnt vmcnt(15)
	v_pk_mul_f32 v[8:9], v[32:33], v[226:227]
	v_pk_mul_f32 v[10:11], v[34:35], v[228:229]
	v_cvt_pk_bf16_f32 v8, v8, v9
	v_cvt_pk_bf16_f32 v9, v10, v11
	global_store_dwordx2 v[30:31], v[8:9], off offset:112
	v_pk_mul_f32 v[32:33], v[40:41], v[46:47] op_sel_hi:[1,0]
	v_pk_mul_f32 v[34:35], v[38:39], v[46:47] op_sel_hi:[1,0]
	s_waitcnt vmcnt(15)
	v_pk_mul_f32 v[8:9], v[32:33], v[230:231]
	v_pk_mul_f32 v[10:11], v[34:35], v[232:233]
	v_cvt_pk_bf16_f32 v8, v8, v9
	v_cvt_pk_bf16_f32 v9, v10, v11
	global_store_dwordx2 v[30:31], v[8:9], off offset:128
	v_pk_mul_f32 v[32:33], v[42:43], v[46:47] op_sel_hi:[1,0]
	s_waitcnt vmcnt(15)
	v_pk_mul_f32 v[10:11], v[16:17], v[236:237]
	v_pk_mul_f32 v[8:9], v[32:33], v[234:235]
	v_pk_mul_f32 v[16:17], v[26:27], v[46:47] op_sel_hi:[1,0]
	v_cvt_pk_bf16_f32 v8, v8, v9
	v_cvt_pk_bf16_f32 v9, v10, v11
	global_store_dwordx2 v[30:31], v[8:9], off offset:144
	s_waitcnt vmcnt(15)
	v_pk_mul_f32 v[8:9], v[16:17], v[238:239]
	v_pk_mul_f32 v[10:11], v[18:19], v[240:241]
	v_cvt_pk_bf16_f32 v8, v8, v9
	v_cvt_pk_bf16_f32 v9, v10, v11
	global_store_dwordx2 v[30:31], v[8:9], off offset:160
	v_pk_mul_f32 v[16:17], v[28:29], v[46:47] op_sel_hi:[1,0]
	v_pk_mul_f32 v[18:19], v[20:21], v[46:47] op_sel_hi:[1,0]
	s_waitcnt vmcnt(15)
	v_pk_mul_f32 v[8:9], v[16:17], v[242:243]
	v_pk_mul_f32 v[10:11], v[18:19], v[244:245]
	v_cvt_pk_bf16_f32 v8, v8, v9
	v_cvt_pk_bf16_f32 v9, v10, v11
	global_store_dwordx2 v[30:31], v[8:9], off offset:176
	v_pk_mul_f32 v[16:17], v[24:25], v[46:47] op_sel_hi:[1,0]
	v_pk_mul_f32 v[18:19], v[22:23], v[46:47] op_sel_hi:[1,0]
	s_waitcnt vmcnt(15)
	v_pk_mul_f32 v[8:9], v[16:17], v[246:247]
	v_pk_mul_f32 v[10:11], v[18:19], v[248:249]
	v_cvt_pk_bf16_f32 v8, v8, v9
	v_cvt_pk_bf16_f32 v9, v10, v11
	global_store_dwordx2 v[30:31], v[8:9], off offset:192
	s_waitcnt vmcnt(12)
	v_pk_mul_f32 v[4:5], v[4:5], v[138:139]
	v_pk_mul_f32 v[0:1], v[0:1], v[140:141]
	v_cvt_pk_bf16_f32 v4, v4, v5
	v_cvt_pk_bf16_f32 v5, v0, v1
	global_store_dwordx2 v[30:31], v[4:5], off offset:208
	v_pk_mul_f32 v[0:1], v[6:7], v[46:47] op_sel_hi:[1,0]
	v_pk_mul_f32 v[4:5], v[12:13], v[46:47] op_sel_hi:[1,0]
	v_pk_mul_f32 v[6:7], v[14:15], v[46:47] op_sel_hi:[1,0]
	s_waitcnt vmcnt(12)
	v_pk_mul_f32 v[0:1], v[0:1], v[142:143]
	v_pk_mul_f32 v[2:3], v[2:3], v[144:145]
	v_cvt_pk_bf16_f32 v0, v0, v1
	v_cvt_pk_bf16_f32 v1, v2, v3
	global_store_dwordx2 v[30:31], v[0:1], off offset:224
	s_waitcnt vmcnt(12)
	v_pk_mul_f32 v[0:1], v[4:5], v[146:147]
	v_pk_mul_f32 v[2:3], v[6:7], v[148:149]
	v_cvt_pk_bf16_f32 v0, v0, v1
	v_cvt_pk_bf16_f32 v1, v2, v3
	global_store_dwordx2 v[30:31], v[0:1], off offset:240
	s_branch .LBB0_479
